# P4 mlstm_out_pair output stage rewritten by hand: o-gate rows requested before the stage barrier, head gains staged in LDS once per pair, no queue drains between the six stores
# speedup vs baseline: 1.0372x; 1.0048x over previous
.LBB0_506:
	s_or_b64 exec, exec, s[36:37]
	s_waitcnt lgkmcnt(0)
	ds_read_b128 v[72:75], v173
	ds_read_b128 v[84:87], v173 offset:6400
	ds_read_b128 v[184:187], v173 offset:12800
	ds_read_b128 v[196:199], v173 offset:19200
	s_mul_i32 s36, s63, 0x60
	s_mulk_i32 s63, 0xc0
	s_lshl_b32 s37, s65, 6
	s_add_i32 s62, s62, s90
	s_waitcnt lgkmcnt(3)
	v_mfma_f32_16x16x32_bf16 v[76:79], v[72:75], v[60:63], 0
	v_mfma_f32_16x16x32_bf16 v[80:83], v[72:75], v[64:67], 0
	v_mfma_f32_16x16x32_bf16 v[72:75], v[72:75], v[68:71], 0
	s_waitcnt lgkmcnt(2)
	v_mfma_f32_16x16x32_bf16 v[176:179], v[84:87], v[60:63], 0
	v_mfma_f32_16x16x32_bf16 v[180:183], v[84:87], v[64:67], 0
	v_mfma_f32_16x16x32_bf16 v[84:87], v[84:87], v[68:71], 0
	s_waitcnt lgkmcnt(1)
	v_mfma_f32_16x16x32_bf16 v[188:191], v[184:187], v[60:63], 0
	v_mfma_f32_16x16x32_bf16 v[192:195], v[184:187], v[64:67], 0
	v_mfma_f32_16x16x32_bf16 v[184:187], v[184:187], v[68:71], 0
	s_waitcnt lgkmcnt(0)
	v_mfma_f32_16x16x32_bf16 v[60:63], v[196:199], v[60:63], 0
	v_mfma_f32_16x16x32_bf16 v[64:67], v[196:199], v[64:67], 0
	v_mfma_f32_16x16x32_bf16 v[68:71], v[196:199], v[68:71], 0
	ds_read_b128 v[196:199], v173 offset:64
	s_waitcnt lgkmcnt(0)
	v_mfma_f32_16x16x32_bf16 v[76:79], v[196:199], v[48:51], v[76:79]
	v_mfma_f32_16x16x32_bf16 v[80:83], v[196:199], v[52:55], v[80:83]
	v_mfma_f32_16x16x32_bf16 v[72:75], v[196:199], v[56:59], v[72:75]
	ds_read_b128 v[196:199], v173 offset:6464
	s_waitcnt lgkmcnt(0)
	v_mfma_f32_16x16x32_bf16 v[176:179], v[196:199], v[48:51], v[176:179]
	v_mfma_f32_16x16x32_bf16 v[180:183], v[196:199], v[52:55], v[180:183]
	v_mfma_f32_16x16x32_bf16 v[84:87], v[196:199], v[56:59], v[84:87]
	ds_read_b128 v[196:199], v173 offset:12864
	s_waitcnt lgkmcnt(0)
	v_mfma_f32_16x16x32_bf16 v[188:191], v[196:199], v[48:51], v[188:191]
	v_mfma_f32_16x16x32_bf16 v[192:195], v[196:199], v[52:55], v[192:195]
	v_mfma_f32_16x16x32_bf16 v[184:187], v[196:199], v[56:59], v[184:187]
	ds_read_b128 v[196:199], v173 offset:19264
	s_waitcnt lgkmcnt(0)
	v_mfma_f32_16x16x32_bf16 v[48:51], v[196:199], v[48:51], v[60:63]
	s_nop 2
	ds_read_b128 v[60:63], v173 offset:128
	v_mfma_f32_16x16x32_bf16 v[52:55], v[196:199], v[52:55], v[64:67]
	v_mfma_f32_16x16x32_bf16 v[56:59], v[196:199], v[56:59], v[68:71]
	s_waitcnt lgkmcnt(0)
	v_mfma_f32_16x16x32_bf16 v[64:67], v[60:63], v[36:39], v[76:79]
	v_mfma_f32_16x16x32_bf16 v[68:71], v[60:63], v[40:43], v[80:83]
	v_mfma_f32_16x16x32_bf16 v[60:63], v[60:63], v[44:47], v[72:75]
	s_nop 2
	ds_read_b128 v[72:75], v173 offset:6528
	s_waitcnt lgkmcnt(0)
	v_mfma_f32_16x16x32_bf16 v[76:79], v[72:75], v[36:39], v[176:179]
	v_mfma_f32_16x16x32_bf16 v[80:83], v[72:75], v[40:43], v[180:183]
	v_mfma_f32_16x16x32_bf16 v[72:75], v[72:75], v[44:47], v[84:87]
	s_nop 2
	ds_read_b128 v[84:87], v173 offset:12928
	s_waitcnt lgkmcnt(0)
	v_mfma_f32_16x16x32_bf16 v[176:179], v[84:87], v[36:39], v[188:191]
	v_mfma_f32_16x16x32_bf16 v[180:183], v[84:87], v[40:43], v[192:195]
	v_mfma_f32_16x16x32_bf16 v[84:87], v[84:87], v[44:47], v[184:187]
	s_nop 2
	ds_read_b128 v[184:187], v173 offset:19328
	s_waitcnt lgkmcnt(0)
	v_mfma_f32_16x16x32_bf16 v[36:39], v[184:187], v[36:39], v[48:51]
	s_nop 2
	ds_read_b128 v[48:51], v173 offset:192
	v_mfma_f32_16x16x32_bf16 v[40:43], v[184:187], v[40:43], v[52:55]
	v_mfma_f32_16x16x32_bf16 v[44:47], v[184:187], v[44:47], v[56:59]
	s_waitcnt lgkmcnt(0)
	v_mfma_f32_16x16x32_bf16 v[52:55], v[48:51], v[24:27], v[64:67]
	v_mfma_f32_16x16x32_bf16 v[56:59], v[48:51], v[28:31], v[68:71]
	v_mfma_f32_16x16x32_bf16 v[48:51], v[48:51], v[32:35], v[60:63]
	s_nop 2
	ds_read_b128 v[60:63], v173 offset:6592
	s_waitcnt lgkmcnt(0)
	v_mfma_f32_16x16x32_bf16 v[64:67], v[60:63], v[24:27], v[76:79]
	v_mfma_f32_16x16x32_bf16 v[68:71], v[60:63], v[28:31], v[80:83]
	v_mfma_f32_16x16x32_bf16 v[60:63], v[60:63], v[32:35], v[72:75]
	s_nop 2
	ds_read_b128 v[72:75], v173 offset:12992
	s_waitcnt lgkmcnt(0)
	v_mfma_f32_16x16x32_bf16 v[76:79], v[72:75], v[24:27], v[176:179]
	v_mfma_f32_16x16x32_bf16 v[80:83], v[72:75], v[28:31], v[180:183]
	v_mfma_f32_16x16x32_bf16 v[72:75], v[72:75], v[32:35], v[84:87]
	s_nop 2
	ds_read_b128 v[84:87], v173 offset:19392
	s_waitcnt lgkmcnt(0)
	v_mfma_f32_16x16x32_bf16 v[24:27], v[84:87], v[24:27], v[36:39]
	s_nop 2
	ds_read_b128 v[36:39], v173 offset:256
	v_mfma_f32_16x16x32_bf16 v[28:31], v[84:87], v[28:31], v[40:43]
	v_mfma_f32_16x16x32_bf16 v[32:35], v[84:87], v[32:35], v[44:47]
	s_waitcnt lgkmcnt(0)
	v_mfma_f32_16x16x32_bf16 v[40:43], v[36:39], v[12:15], v[52:55]
	v_mfma_f32_16x16x32_bf16 v[44:47], v[36:39], v[16:19], v[56:59]
	v_mfma_f32_16x16x32_bf16 v[36:39], v[36:39], v[20:23], v[48:51]
	s_nop 2
	ds_read_b128 v[48:51], v173 offset:6656
	s_waitcnt lgkmcnt(0)
	v_mfma_f32_16x16x32_bf16 v[52:55], v[48:51], v[12:15], v[64:67]
	v_mfma_f32_16x16x32_bf16 v[56:59], v[48:51], v[16:19], v[68:71]
	v_mfma_f32_16x16x32_bf16 v[48:51], v[48:51], v[20:23], v[60:63]
	s_nop 2
	ds_read_b128 v[60:63], v173 offset:13056
	s_waitcnt lgkmcnt(0)
	v_mfma_f32_16x16x32_bf16 v[64:67], v[60:63], v[12:15], v[76:79]
	v_mfma_f32_16x16x32_bf16 v[68:71], v[60:63], v[16:19], v[80:83]
	v_mfma_f32_16x16x32_bf16 v[60:63], v[60:63], v[20:23], v[72:75]
	s_nop 2
	ds_read_b128 v[72:75], v173 offset:19456
	s_waitcnt lgkmcnt(0)
	v_mfma_f32_16x16x32_bf16 v[12:15], v[72:75], v[12:15], v[24:27]
	s_nop 2
	ds_read_b128 v[24:27], v173 offset:320
	v_mfma_f32_16x16x32_bf16 v[16:19], v[72:75], v[16:19], v[28:31]
	v_mfma_f32_16x16x32_bf16 v[20:23], v[72:75], v[20:23], v[32:35]
	s_waitcnt lgkmcnt(0)
	v_mfma_f32_16x16x32_bf16 v[28:31], v[24:27], v[0:3], v[40:43]
	v_mfma_f32_16x16x32_bf16 v[32:35], v[24:27], v[4:7], v[44:47]
	v_mfma_f32_16x16x32_bf16 v[24:27], v[24:27], v[8:11], v[36:39]
	s_nop 2
	ds_read_b128 v[36:39], v173 offset:6720
	s_waitcnt lgkmcnt(0)
	v_mfma_f32_16x16x32_bf16 v[40:43], v[36:39], v[0:3], v[52:55]
	v_mfma_f32_16x16x32_bf16 v[44:47], v[36:39], v[4:7], v[56:59]
	v_mfma_f32_16x16x32_bf16 v[36:39], v[36:39], v[8:11], v[48:51]
	s_nop 2
	ds_read_b128 v[48:51], v173 offset:13120
	s_waitcnt lgkmcnt(0)
	v_mfma_f32_16x16x32_bf16 v[52:55], v[48:51], v[0:3], v[64:67]
	v_mfma_f32_16x16x32_bf16 v[56:59], v[48:51], v[4:7], v[68:71]
	v_mfma_f32_16x16x32_bf16 v[48:51], v[48:51], v[8:11], v[60:63]
	s_nop 1
	v_add_u32_e32 v68, s36, v141
	v_lshl_add_u32 v69, s64, 5, v141
	v_lshl_add_u32 v70, s65, 5, v141
	ds_read_b128 v[60:63], v173 offset:19520
	s_waitcnt lgkmcnt(0)
	v_mfma_f32_16x16x32_bf16 v[0:3], v[60:63], v[0:3], v[12:15]
	s_nop 2
	ds_read_b128 v[12:15], v94 offset:60928
	s_lshl_b32 s36, s64, 6
	s_cmpk_lt_i32 s62, 0x400
	v_mfma_f32_16x16x32_bf16 v[4:7], v[60:63], v[4:7], v[16:19]
	v_mfma_f32_16x16x32_bf16 v[8:11], v[60:63], v[8:11], v[20:23]
	s_waitcnt lgkmcnt(0)
	s_nop 0
	v_pk_mul_f32 v[18:19], v[30:31], v[14:15]
	v_pk_mul_f32 v[16:17], v[28:29], v[12:13]
	v_pk_mul_f32 v[22:23], v[34:35], v[14:15]
	v_pk_mul_f32 v[20:21], v[32:33], v[12:13]
	v_pk_mul_f32 v[14:15], v[26:27], v[14:15]
	v_pk_mul_f32 v[12:13], v[24:25], v[12:13]
	ds_read_b128 v[24:27], v94 offset:60992
	s_waitcnt lgkmcnt(0)
	v_pk_mul_f32 v[30:31], v[42:43], v[26:27]
	v_pk_mul_f32 v[28:29], v[40:41], v[24:25]
	v_pk_mul_f32 v[34:35], v[46:47], v[26:27]
	v_pk_mul_f32 v[32:33], v[44:45], v[24:25]
	v_pk_mul_f32 v[26:27], v[38:39], v[26:27]
	v_pk_mul_f32 v[24:25], v[36:37], v[24:25]
	ds_read_b128 v[36:39], v94 offset:61056
	s_waitcnt lgkmcnt(0)
	v_pk_mul_f32 v[42:43], v[54:55], v[38:39]
	v_pk_mul_f32 v[40:41], v[52:53], v[36:37]
	v_pk_mul_f32 v[46:47], v[58:59], v[38:39]
	v_pk_mul_f32 v[44:45], v[56:57], v[36:37]
	v_pk_mul_f32 v[38:39], v[50:51], v[38:39]
	v_pk_mul_f32 v[36:37], v[48:49], v[36:37]
	ds_read_b128 v[48:51], v94 offset:61120
	s_waitcnt lgkmcnt(0)
	s_barrier
	v_pk_mul_f32 v[2:3], v[2:3], v[50:51]
	v_pk_mul_f32 v[0:1], v[0:1], v[48:49]
	v_pk_mul_f32 v[6:7], v[6:7], v[50:51]
	v_pk_mul_f32 v[4:5], v[4:5], v[48:49]
	v_pk_mul_f32 v[10:11], v[10:11], v[50:51]
	v_pk_mul_f32 v[8:9], v[8:9], v[48:49]
	ds_read_b64_tr_b16 v[48:49], v68 offset:25600
	ds_read_b64_tr_b16 v[50:51], v68 offset:27200
	ds_read_b64_tr_b16 v[52:53], v69 offset:25600
	ds_read_b64_tr_b16 v[54:55], v69 offset:27200
	ds_read_b64_tr_b16 v[56:57], v70 offset:25600
	ds_read_b64_tr_b16 v[58:59], v70 offset:27200
	ds_read_b128 v[60:63], v166 offset:51200
	s_waitcnt lgkmcnt(0)
	v_mfma_f32_16x16x32_bf16 v[16:19], v[60:63], v[48:51], v[16:19]
	v_mfma_f32_16x16x32_bf16 v[20:23], v[60:63], v[52:55], v[20:23]
	v_mfma_f32_16x16x32_bf16 v[12:15], v[60:63], v[56:59], v[12:15]
	ds_read_b128 v[60:63], v166 offset:53504
	s_waitcnt lgkmcnt(0)
	v_mfma_f32_16x16x32_bf16 v[64:67], v[60:63], v[52:55], v[32:35]
	s_nop 2
	ds_read_b128 v[32:35], v166 offset:55808
	s_waitcnt lgkmcnt(0)
	v_mfma_f32_16x16x32_bf16 v[40:43], v[32:35], v[48:51], v[40:43]
	v_mfma_f32_16x16x32_bf16 v[44:47], v[32:35], v[52:55], v[44:47]
	v_mfma_f32_16x16x32_bf16 v[36:39], v[32:35], v[56:59], v[36:39]
	ds_read_b128 v[32:35], v166 offset:58112
	v_mfma_f32_16x16x32_bf16 v[28:31], v[60:63], v[48:51], v[28:31]
	v_mfma_f32_16x16x32_bf16 v[24:27], v[60:63], v[56:59], v[24:27]
	s_waitcnt lgkmcnt(0)
	v_mfma_f32_16x16x32_bf16 v[0:3], v[32:35], v[48:51], v[0:3]
	v_mfma_f32_16x16x32_bf16 v[4:7], v[32:35], v[52:55], v[4:7]
	v_mfma_f32_16x16x32_bf16 v[48:51], v[32:35], v[56:59], v[8:11]
	s_nop 2
	ds_read_b64_tr_b16 v[8:9], v68 offset:38400
	ds_read_b64_tr_b16 v[10:11], v68 offset:40000
	ds_read_b64_tr_b16 v[52:53], v69 offset:38400
	ds_read_b64_tr_b16 v[54:55], v69 offset:40000
	ds_read_b64_tr_b16 v[56:57], v70 offset:38400
	ds_read_b64_tr_b16 v[58:59], v70 offset:40000
	ds_read_b128 v[32:35], v166 offset:51264
	s_waitcnt lgkmcnt(0)
	v_mfma_f32_16x16x32_bf16 v[72:75], v[32:35], v[56:59], v[12:15]
	s_nop 2
	ds_read_b128 v[12:15], v166 offset:53568
	v_mfma_f32_16x16x32_bf16 v[60:63], v[32:35], v[8:11], v[16:19]
	v_mfma_f32_16x16x32_bf16 v[68:71], v[32:35], v[52:55], v[20:23]
	s_waitcnt lgkmcnt(0)
	v_mfma_f32_16x16x32_bf16 v[32:35], v[12:15], v[8:11], v[28:31]
	v_mfma_f32_16x16x32_bf16 v[28:31], v[12:15], v[52:55], v[64:67]
	v_mfma_f32_16x16x32_bf16 v[24:27], v[12:15], v[56:59], v[24:27]
	ds_read_b128 v[12:15], v166 offset:55872
	s_waitcnt lgkmcnt(0)
	v_mfma_f32_16x16x32_bf16 v[20:23], v[12:15], v[8:11], v[40:43]
	v_mfma_f32_16x16x32_bf16 v[16:19], v[12:15], v[52:55], v[44:47]
	v_mfma_f32_16x16x32_bf16 v[12:15], v[12:15], v[56:59], v[36:39]
	s_nop 2
	ds_read_b128 v[36:39], v166 offset:58176
	s_waitcnt lgkmcnt(0)
	v_mfma_f32_16x16x32_bf16 v[8:11], v[36:39], v[8:11], v[0:3]
	s_barrier
	v_mfma_f32_16x16x32_bf16 v[4:7], v[36:39], v[52:55], v[4:7]
	v_mfma_f32_16x16x32_bf16 v[0:3], v[36:39], v[56:59], v[48:51]
	ds_read_b32 v36, v94 offset:61440
	v_add_u32_e32 v38, s63, v142
	s_waitcnt lgkmcnt(0)
	v_mul_f32_e32 v37, v60, v36
	ds_write_b32 v38, v37
	v_mul_f32_e32 v37, v68, v36
	v_add_u32_e32 v38, s36, v142
	ds_write_b32 v38, v37
	v_mul_f32_e32 v36, v72, v36
	v_add_u32_e32 v37, s37, v142
	ds_write_b32 v37, v36
	ds_read_b32 v36, v94 offset:61444
	v_add_u32_e32 v38, s63, v143
	s_waitcnt lgkmcnt(0)
	v_mul_f32_e32 v37, v61, v36
	ds_write_b32 v38, v37
	v_mul_f32_e32 v37, v69, v36
	v_add_u32_e32 v38, s36, v143
	ds_write_b32 v38, v37
	v_mul_f32_e32 v36, v73, v36
	v_add_u32_e32 v37, s37, v143
	ds_write_b32 v37, v36
	ds_read_b32 v36, v94 offset:61448
	v_add_u32_e32 v38, s63, v144
	s_waitcnt lgkmcnt(0)
	v_mul_f32_e32 v37, v62, v36
	ds_write_b32 v38, v37
	v_mul_f32_e32 v37, v70, v36
	v_add_u32_e32 v38, s36, v144
	ds_write_b32 v38, v37
	v_mul_f32_e32 v36, v74, v36
	v_add_u32_e32 v37, s37, v144
	ds_write_b32 v37, v36
	ds_read_b32 v36, v94 offset:61452
	v_add_u32_e32 v38, s63, v145
	s_waitcnt lgkmcnt(0)
	v_mul_f32_e32 v37, v63, v36
	ds_write_b32 v38, v37
	v_mul_f32_e32 v37, v71, v36
	v_add_u32_e32 v38, s36, v145
	ds_write_b32 v38, v37
	v_mul_f32_e32 v36, v75, v36
	v_add_u32_e32 v37, s37, v145
	ds_write_b32 v37, v36
	ds_read_b32 v36, v94 offset:61504
	v_add_u32_e32 v37, s63, v146
	s_waitcnt lgkmcnt(0)
	v_mul_f32_e32 v32, v32, v36
	ds_write_b32 v37, v32
	v_mul_f32_e32 v28, v28, v36
	v_add_u32_e32 v32, s36, v146
	ds_write_b32 v32, v28
	v_mul_f32_e32 v24, v24, v36
	v_add_u32_e32 v28, s37, v146
	ds_write_b32 v28, v24
	ds_read_b32 v24, v94 offset:61508
	v_add_u32_e32 v32, s63, v147
	s_waitcnt lgkmcnt(0)
	v_mul_f32_e32 v28, v33, v24
	ds_write_b32 v32, v28
	v_mul_f32_e32 v28, v29, v24
	v_add_u32_e32 v29, s36, v147
	v_mul_f32_e32 v24, v25, v24
	v_add_u32_e32 v25, s37, v147
	ds_write_b32 v29, v28
	ds_write_b32 v25, v24
	ds_read_b32 v24, v94 offset:61512
	v_add_u32_e32 v28, s63, v148
	s_waitcnt lgkmcnt(0)
	v_mul_f32_e32 v25, v34, v24
	ds_write_b32 v28, v25
	v_mul_f32_e32 v25, v30, v24
	v_add_u32_e32 v28, s36, v148
	ds_write_b32 v28, v25
	v_mul_f32_e32 v24, v26, v24
	v_add_u32_e32 v25, s37, v148
	ds_write_b32 v25, v24
	ds_read_b32 v24, v94 offset:61516
	v_add_u32_e32 v26, s63, v149
	s_waitcnt lgkmcnt(0)
	v_mul_f32_e32 v25, v35, v24
	ds_write_b32 v26, v25
	v_mul_f32_e32 v25, v31, v24
	v_add_u32_e32 v26, s36, v149
	ds_write_b32 v26, v25
	v_mul_f32_e32 v24, v27, v24
	v_add_u32_e32 v25, s37, v149
	ds_write_b32 v25, v24
	ds_read_b32 v24, v94 offset:61568
	v_add_u32_e32 v25, s63, v150
	s_waitcnt lgkmcnt(0)
	v_mul_f32_e32 v20, v20, v24
	ds_write_b32 v25, v20
	v_mul_f32_e32 v16, v16, v24
	v_add_u32_e32 v20, s36, v150
	ds_write_b32 v20, v16
	v_mul_f32_e32 v12, v12, v24
	v_add_u32_e32 v16, s37, v150
	ds_write_b32 v16, v12
	ds_read_b32 v12, v94 offset:61572
	v_add_u32_e32 v20, s63, v151
	s_waitcnt lgkmcnt(0)
	v_mul_f32_e32 v16, v21, v12
	ds_write_b32 v20, v16
	v_mul_f32_e32 v16, v17, v12
	v_add_u32_e32 v17, s36, v151
	v_mul_f32_e32 v12, v13, v12
	v_add_u32_e32 v13, s37, v151
	ds_write_b32 v17, v16
	ds_write_b32 v13, v12
	ds_read_b32 v12, v94 offset:61576
	v_add_u32_e32 v16, s63, v152
	s_waitcnt lgkmcnt(0)
	v_mul_f32_e32 v13, v22, v12
	ds_write_b32 v16, v13
	v_mul_f32_e32 v13, v18, v12
	v_add_u32_e32 v16, s36, v152
	ds_write_b32 v16, v13
	v_mul_f32_e32 v12, v14, v12
	v_add_u32_e32 v13, s37, v152
	ds_write_b32 v13, v12
	ds_read_b32 v12, v94 offset:61580
	v_add_u32_e32 v14, s63, v153
	s_waitcnt lgkmcnt(0)
	v_mul_f32_e32 v13, v23, v12
	ds_write_b32 v14, v13
	v_mul_f32_e32 v13, v19, v12
	v_add_u32_e32 v14, s36, v153
	ds_write_b32 v14, v13
	v_mul_f32_e32 v12, v15, v12
	v_add_u32_e32 v13, s37, v153
	ds_write_b32 v13, v12
	ds_read_b32 v12, v94 offset:61632
	v_add_u32_e32 v13, s63, v154
	s_waitcnt lgkmcnt(0)
	v_mul_f32_e32 v8, v8, v12
	ds_write_b32 v13, v8
	v_mul_f32_e32 v4, v4, v12
	v_add_u32_e32 v8, s36, v154
	ds_write_b32 v8, v4
	v_mul_f32_e32 v0, v0, v12
	v_add_u32_e32 v4, s37, v154
	ds_write_b32 v4, v0
	ds_read_b32 v0, v94 offset:61636
	v_add_u32_e32 v8, s63, v155
	s_waitcnt lgkmcnt(0)
	v_mul_f32_e32 v4, v9, v0
	ds_write_b32 v8, v4
	v_mul_f32_e32 v4, v5, v0
	v_add_u32_e32 v5, s36, v155
	v_mul_f32_e32 v0, v1, v0
	v_add_u32_e32 v1, s37, v155
	ds_write_b32 v5, v4
	ds_write_b32 v1, v0
	ds_read_b32 v0, v94 offset:61640
	v_add_u32_e32 v4, s63, v156
	s_waitcnt lgkmcnt(0)
	v_mul_f32_e32 v1, v10, v0
	ds_write_b32 v4, v1
	v_mul_f32_e32 v1, v6, v0
	v_add_u32_e32 v4, s36, v156
	ds_write_b32 v4, v1
	v_mul_f32_e32 v0, v2, v0
	v_add_u32_e32 v1, s37, v156
	ds_write_b32 v1, v0
	ds_read_b32 v0, v94 offset:61644
	v_add_u32_e32 v2, s63, v157
	s_waitcnt lgkmcnt(0)
	v_mul_f32_e32 v1, v11, v0
	ds_write_b32 v2, v1
	v_mul_f32_e32 v1, v7, v0
	v_add_u32_e32 v2, s36, v157
	ds_write_b32 v2, v1
	v_mul_f32_e32 v0, v3, v0
	v_add_u32_e32 v1, s37, v157
	ds_write_b32 v1, v0
	ds_write_b32 v101, v246 offset:62464
	v_or_b32_e32 v202, v125, v108
	v_mov_b64_e32 v[200:201], s[60:61]
	v_mad_u64_u32 v[200:201], vcc, v202, s50, v[200:201]
	v_mov_b32_e32 v202, v201
	v_mad_u64_u32 v[202:203], vcc, v127, s50, v[202:203]
	v_mov_b32_e32 v201, v202
	v_lshl_add_u64 v[200:201], v[200:201], 0, v[90:91]
	v_mov_b32_e32 v202, v124
	v_mov_b32_e32 v203, v91
	v_lshl_add_u64 v[200:201], v[200:201], 0, v[202:203]
	v_lshl_add_u64 v[200:201], v[200:201], 0, s[34:35]
	global_load_dwordx4 v[206:209], v[200:201], off
	global_load_dwordx4 v[210:213], v[200:201], off offset:16
	global_load_dwordx4 v[214:217], v[200:201], off offset:32
	global_load_dwordx4 v[218:221], v[200:201], off offset:48
	global_load_dwordx4 v[222:225], v[200:201], off offset:64
	global_load_dwordx4 v[226:229], v[200:201], off offset:80
	s_waitcnt lgkmcnt(0)
	s_barrier
	ds_read_b128 v[8:11], v167
	ds_read_b128 v[18:21], v167 offset:16
	ds_read_b128 v[22:25], v167 offset:32
	ds_read_b128 v[4:7], v167 offset:48
	s_waitcnt lgkmcnt(3)
	v_mul_f32_e32 v0, v9, v9
	v_pk_fma_f32 v[0:1], v[8:9], v[8:9], v[0:1] op_sel_hi:[1,1,0]
	s_waitcnt lgkmcnt(1)
	v_mul_f32_e32 v2, v22, v22
	v_mov_b32_e32 v1, v2
	v_mul_f32_e32 v2, v11, v11
	v_mul_f32_e32 v12, v23, v23
	v_pk_fma_f32 v[2:3], v[10:11], v[10:11], v[2:3] op_sel_hi:[1,1,0]
	v_mul_f32_e32 v13, v24, v24
	v_mov_b32_e32 v3, v12
	v_pk_add_f32 v[0:1], v[0:1], v[2:3]
	v_mul_f32_e32 v2, v19, v19
	v_pk_fma_f32 v[2:3], v[18:19], v[18:19], v[2:3] op_sel_hi:[1,1,0]
	v_mul_f32_e32 v12, v21, v21
	v_mul_f32_e32 v14, v25, v25
	v_mov_b32_e32 v3, v13
	v_pk_fma_f32 v[12:13], v[20:21], v[20:21], v[12:13] op_sel_hi:[1,1,0]
	s_nop 0
	v_mov_b32_e32 v13, v14
	v_pk_add_f32 v[2:3], v[2:3], v[12:13]
	s_nop 0
	v_pk_add_f32 v[16:17], v[0:1], v[2:3]
	s_waitcnt lgkmcnt(0)
	v_pk_mul_f32 v[0:1], v[6:7], v[6:7]
	v_pk_mul_f32 v[2:3], v[4:5], v[4:5]
	s_nop 0
	v_pk_mov_b32 v[12:13], v[2:3], v[0:1] op_sel:[1,0]
	v_mov_b32_e32 v3, v1
	v_pk_add_f32 v[26:27], v[12:13], v[2:3]
	ds_read_b128 v[0:3], v167 offset:64
	ds_read_b128 v[12:15], v167 offset:80
	s_waitcnt lgkmcnt(0)
	v_mul_f32_e32 v28, v12, v12
	v_mul_f32_e32 v29, v13, v13
	v_mul_f32_e32 v30, v14, v14
	v_mul_f32_e32 v31, v15, v15
	v_pk_add_f32 v[12:13], v[16:17], v[16:17] op_sel:[0,1] op_sel_hi:[1,0]
	v_pk_add_f32 v[14:15], v[26:27], v[26:27] op_sel:[0,1] op_sel_hi:[1,0]
	v_mov_b32_e32 v13, v28
	v_mov_b32_e32 v15, v29
	v_pk_add_f32 v[12:13], v[12:13], v[14:15]
	v_mul_f32_e32 v14, v1, v1
	v_pk_fma_f32 v[0:1], v[0:1], v[0:1], v[14:15] op_sel_hi:[1,1,0]
	v_mul_f32_e32 v14, v3, v3
	v_pk_fma_f32 v[2:3], v[2:3], v[2:3], v[14:15] op_sel_hi:[1,1,0]
	v_mov_b32_e32 v1, v30
	v_mov_b32_e32 v3, v31
	v_pk_add_f32 v[0:1], v[0:1], v[2:3]
	s_nop 0
	v_pk_add_f32 v[16:17], v[12:13], v[0:1]
	ds_read_b128 v[0:3], v167 offset:96
	s_waitcnt lgkmcnt(0)
	v_pk_mul_f32 v[2:3], v[2:3], v[2:3]
	v_pk_mul_f32 v[0:1], v[0:1], v[0:1]
	s_nop 0
	v_pk_mov_b32 v[12:13], v[0:1], v[2:3] op_sel:[1,0]
	v_mov_b32_e32 v1, v3
	v_pk_add_f32 v[26:27], v[12:13], v[0:1]
	ds_read_b128 v[0:3], v167 offset:112
	ds_read_b128 v[12:15], v167 offset:128
	s_waitcnt lgkmcnt(0)
	v_mul_f32_e32 v28, v12, v12
	v_mul_f32_e32 v29, v13, v13
	v_mul_f32_e32 v30, v14, v14
	v_mul_f32_e32 v31, v15, v15
	v_pk_add_f32 v[12:13], v[16:17], v[16:17] op_sel:[0,1] op_sel_hi:[1,0]
	v_pk_add_f32 v[14:15], v[26:27], v[26:27] op_sel:[0,1] op_sel_hi:[1,0]
	v_mov_b32_e32 v13, v28
	v_mov_b32_e32 v15, v29
	v_pk_add_f32 v[12:13], v[12:13], v[14:15]
	v_mul_f32_e32 v14, v1, v1
	v_pk_fma_f32 v[0:1], v[0:1], v[0:1], v[14:15] op_sel_hi:[1,1,0]
	v_mul_f32_e32 v14, v3, v3
	v_pk_fma_f32 v[2:3], v[2:3], v[2:3], v[14:15] op_sel_hi:[1,1,0]
	v_mov_b32_e32 v1, v30
	v_mov_b32_e32 v3, v31
	v_pk_add_f32 v[0:1], v[0:1], v[2:3]
	s_nop 0
	v_pk_add_f32 v[16:17], v[12:13], v[0:1]
	ds_read_b128 v[0:3], v167 offset:144
	s_waitcnt lgkmcnt(0)
	v_pk_mul_f32 v[2:3], v[2:3], v[2:3]
	v_pk_mul_f32 v[0:1], v[0:1], v[0:1]
	s_nop 0
	v_pk_mov_b32 v[12:13], v[0:1], v[2:3] op_sel:[1,0]
	v_mov_b32_e32 v1, v3
	v_pk_add_f32 v[26:27], v[12:13], v[0:1]
	ds_read_b128 v[0:3], v167 offset:160
	ds_read_b128 v[12:15], v167 offset:176
	s_waitcnt lgkmcnt(0)
	v_mul_f32_e32 v28, v12, v12
	v_mul_f32_e32 v29, v13, v13
	v_mul_f32_e32 v30, v14, v14
	v_mul_f32_e32 v31, v15, v15
	v_pk_add_f32 v[12:13], v[16:17], v[16:17] op_sel:[0,1] op_sel_hi:[1,0]
	v_pk_add_f32 v[14:15], v[26:27], v[26:27] op_sel:[0,1] op_sel_hi:[1,0]
	v_mov_b32_e32 v13, v28
	v_mov_b32_e32 v15, v29
	v_pk_add_f32 v[12:13], v[12:13], v[14:15]
	v_mul_f32_e32 v14, v1, v1
	v_pk_fma_f32 v[0:1], v[0:1], v[0:1], v[14:15] op_sel_hi:[1,1,0]
	v_mul_f32_e32 v14, v3, v3
	v_pk_fma_f32 v[2:3], v[2:3], v[2:3], v[14:15] op_sel_hi:[1,1,0]
	v_mov_b32_e32 v1, v30
	v_mov_b32_e32 v3, v31
	v_pk_add_f32 v[0:1], v[0:1], v[2:3]
	v_pk_add_f32 v[0:1], v[12:13], v[0:1]
	v_add_f32_e32 v0, v0, v1
	ds_bpermute_b32 v1, v139, v0
	s_waitcnt lgkmcnt(0)
	v_add_f32_e32 v0, v0, v1
	ds_bpermute_b32 v1, v140, v0
	s_waitcnt lgkmcnt(0)
	v_add_f32_e32 v0, v0, v1
	v_fmamk_f32 v0, v0, 0x3baaaaab, v168
	v_cmp_gt_f32_e32 vcc, s55, v0
	v_mul_f32_e32 v1, 0x4b800000, v0
	s_nop 0
	v_cndmask_b32_e32 v0, v0, v1, vcc
	v_rsq_f32_e32 v0, v0
	s_nop 0
	v_mul_f32_e32 v1, 0x45800000, v0
	v_cndmask_b32_e32 v14, v0, v1, vcc
	ds_read_b128 v[0:3], v167 offset:0
	ds_read_b128 v[4:7], v167 offset:16
	ds_read_b128 v[16:19], v138 offset:62464
	ds_read_b128 v[20:23], v138 offset:62480
	ds_read_b128 v[32:35], v167 offset:32
	ds_read_b128 v[36:39], v167 offset:48
	ds_read_b128 v[40:43], v138 offset:62496
	ds_read_b128 v[44:47], v138 offset:62512
	s_waitcnt vmcnt(5)
	v_lshlrev_b32_e32 v24, 16, v206
	v_and_b32_e32 v25, 0xffff0000, v206
	v_lshlrev_b32_e32 v26, 16, v207
	v_and_b32_e32 v27, 0xffff0000, v207
	v_lshlrev_b32_e32 v28, 16, v208
	v_and_b32_e32 v29, 0xffff0000, v208
	v_lshlrev_b32_e32 v30, 16, v209
	v_and_b32_e32 v31, 0xffff0000, v209
	v_mul_f32_e32 v24, 0xbfb8aa3b, v24
	v_mul_f32_e32 v25, 0xbfb8aa3b, v25
	v_mul_f32_e32 v26, 0xbfb8aa3b, v26
	v_mul_f32_e32 v27, 0xbfb8aa3b, v27
	v_mul_f32_e32 v28, 0xbfb8aa3b, v28
	v_mul_f32_e32 v29, 0xbfb8aa3b, v29
	v_mul_f32_e32 v30, 0xbfb8aa3b, v30
	v_mul_f32_e32 v31, 0xbfb8aa3b, v31
	v_exp_f32_e32 v24, v24
	v_exp_f32_e32 v25, v25
	v_exp_f32_e32 v26, v26
	v_exp_f32_e32 v27, v27
	v_exp_f32_e32 v28, v28
	v_exp_f32_e32 v29, v29
	v_exp_f32_e32 v30, v30
	v_exp_f32_e32 v31, v31
	v_add_f32_e32 v24, 1.0, v24
	v_add_f32_e32 v25, 1.0, v25
	v_add_f32_e32 v26, 1.0, v26
	v_add_f32_e32 v27, 1.0, v27
	v_add_f32_e32 v28, 1.0, v28
	v_add_f32_e32 v29, 1.0, v29
	v_add_f32_e32 v30, 1.0, v30
	v_add_f32_e32 v31, 1.0, v31
	v_rcp_f32_e32 v24, v24
	v_rcp_f32_e32 v25, v25
	v_rcp_f32_e32 v26, v26
	v_rcp_f32_e32 v27, v27
	v_rcp_f32_e32 v28, v28
	v_rcp_f32_e32 v29, v29
	v_rcp_f32_e32 v30, v30
	v_rcp_f32_e32 v31, v31
	s_waitcnt lgkmcnt(4)
	v_pk_mul_f32 v[0:1], v[0:1], v[14:15] op_sel_hi:[1,0]
	v_pk_mul_f32 v[2:3], v[2:3], v[14:15] op_sel_hi:[1,0]
	v_pk_mul_f32 v[4:5], v[4:5], v[14:15] op_sel_hi:[1,0]
	v_pk_mul_f32 v[6:7], v[6:7], v[14:15] op_sel_hi:[1,0]
	v_pk_mul_f32 v[0:1], v[16:17], v[0:1]
	v_pk_mul_f32 v[2:3], v[18:19], v[2:3]
	v_pk_mul_f32 v[4:5], v[20:21], v[4:5]
	v_pk_mul_f32 v[6:7], v[22:23], v[6:7]
	v_pk_mul_f32 v[0:1], v[24:25], v[0:1]
	v_pk_mul_f32 v[2:3], v[26:27], v[2:3]
	v_pk_mul_f32 v[4:5], v[28:29], v[4:5]
	v_pk_mul_f32 v[6:7], v[30:31], v[6:7]
	v_cvt_pk_bf16_f32 v8, v0, v1
	v_cvt_pk_bf16_f32 v9, v2, v3
	v_cvt_pk_bf16_f32 v10, v4, v5
	v_cvt_pk_bf16_f32 v11, v6, v7
	global_store_dwordx4 v[200:201], v[8:11], off
	ds_read_b128 v[0:3], v167 offset:64
	ds_read_b128 v[4:7], v167 offset:80
	ds_read_b128 v[16:19], v138 offset:62528
	ds_read_b128 v[20:23], v138 offset:62544
	s_waitcnt vmcnt(5)
	v_lshlrev_b32_e32 v24, 16, v210
	v_and_b32_e32 v25, 0xffff0000, v210
	v_lshlrev_b32_e32 v26, 16, v211
	v_and_b32_e32 v27, 0xffff0000, v211
	v_lshlrev_b32_e32 v28, 16, v212
	v_and_b32_e32 v29, 0xffff0000, v212
	v_lshlrev_b32_e32 v30, 16, v213
	v_and_b32_e32 v31, 0xffff0000, v213
	v_mul_f32_e32 v24, 0xbfb8aa3b, v24
	v_mul_f32_e32 v25, 0xbfb8aa3b, v25
	v_mul_f32_e32 v26, 0xbfb8aa3b, v26
	v_mul_f32_e32 v27, 0xbfb8aa3b, v27
	v_mul_f32_e32 v28, 0xbfb8aa3b, v28
	v_mul_f32_e32 v29, 0xbfb8aa3b, v29
	v_mul_f32_e32 v30, 0xbfb8aa3b, v30
	v_mul_f32_e32 v31, 0xbfb8aa3b, v31
	v_exp_f32_e32 v24, v24
	v_exp_f32_e32 v25, v25
	v_exp_f32_e32 v26, v26
	v_exp_f32_e32 v27, v27
	v_exp_f32_e32 v28, v28
	v_exp_f32_e32 v29, v29
	v_exp_f32_e32 v30, v30
	v_exp_f32_e32 v31, v31
	v_add_f32_e32 v24, 1.0, v24
	v_add_f32_e32 v25, 1.0, v25
	v_add_f32_e32 v26, 1.0, v26
	v_add_f32_e32 v27, 1.0, v27
	v_add_f32_e32 v28, 1.0, v28
	v_add_f32_e32 v29, 1.0, v29
	v_add_f32_e32 v30, 1.0, v30
	v_add_f32_e32 v31, 1.0, v31
	v_rcp_f32_e32 v24, v24
	v_rcp_f32_e32 v25, v25
	v_rcp_f32_e32 v26, v26
	v_rcp_f32_e32 v27, v27
	v_rcp_f32_e32 v28, v28
	v_rcp_f32_e32 v29, v29
	v_rcp_f32_e32 v30, v30
	v_rcp_f32_e32 v31, v31
	s_waitcnt lgkmcnt(4)
	v_pk_mul_f32 v[32:33], v[32:33], v[14:15] op_sel_hi:[1,0]
	v_pk_mul_f32 v[34:35], v[34:35], v[14:15] op_sel_hi:[1,0]
	v_pk_mul_f32 v[36:37], v[36:37], v[14:15] op_sel_hi:[1,0]
	v_pk_mul_f32 v[38:39], v[38:39], v[14:15] op_sel_hi:[1,0]
	v_pk_mul_f32 v[32:33], v[40:41], v[32:33]
	v_pk_mul_f32 v[34:35], v[42:43], v[34:35]
	v_pk_mul_f32 v[36:37], v[44:45], v[36:37]
	v_pk_mul_f32 v[38:39], v[46:47], v[38:39]
	v_pk_mul_f32 v[32:33], v[24:25], v[32:33]
	v_pk_mul_f32 v[34:35], v[26:27], v[34:35]
	v_pk_mul_f32 v[36:37], v[28:29], v[36:37]
	v_pk_mul_f32 v[38:39], v[30:31], v[38:39]
	v_cvt_pk_bf16_f32 v8, v32, v33
	v_cvt_pk_bf16_f32 v9, v34, v35
	v_cvt_pk_bf16_f32 v10, v36, v37
	v_cvt_pk_bf16_f32 v11, v38, v39
	global_store_dwordx4 v[200:201], v[8:11], off offset:16
	ds_read_b128 v[32:35], v167 offset:96
	ds_read_b128 v[36:39], v167 offset:112
	ds_read_b128 v[40:43], v138 offset:62560
	ds_read_b128 v[44:47], v138 offset:62576
	s_waitcnt vmcnt(5)
	v_lshlrev_b32_e32 v24, 16, v214
	v_and_b32_e32 v25, 0xffff0000, v214
	v_lshlrev_b32_e32 v26, 16, v215
	v_and_b32_e32 v27, 0xffff0000, v215
	v_lshlrev_b32_e32 v28, 16, v216
	v_and_b32_e32 v29, 0xffff0000, v216
	v_lshlrev_b32_e32 v30, 16, v217
	v_and_b32_e32 v31, 0xffff0000, v217
	v_mul_f32_e32 v24, 0xbfb8aa3b, v24
	v_mul_f32_e32 v25, 0xbfb8aa3b, v25
	v_mul_f32_e32 v26, 0xbfb8aa3b, v26
	v_mul_f32_e32 v27, 0xbfb8aa3b, v27
	v_mul_f32_e32 v28, 0xbfb8aa3b, v28
	v_mul_f32_e32 v29, 0xbfb8aa3b, v29
	v_mul_f32_e32 v30, 0xbfb8aa3b, v30
	v_mul_f32_e32 v31, 0xbfb8aa3b, v31
	v_exp_f32_e32 v24, v24
	v_exp_f32_e32 v25, v25
	v_exp_f32_e32 v26, v26
	v_exp_f32_e32 v27, v27
	v_exp_f32_e32 v28, v28
	v_exp_f32_e32 v29, v29
	v_exp_f32_e32 v30, v30
	v_exp_f32_e32 v31, v31
	v_add_f32_e32 v24, 1.0, v24
	v_add_f32_e32 v25, 1.0, v25
	v_add_f32_e32 v26, 1.0, v26
	v_add_f32_e32 v27, 1.0, v27
	v_add_f32_e32 v28, 1.0, v28
	v_add_f32_e32 v29, 1.0, v29
	v_add_f32_e32 v30, 1.0, v30
	v_add_f32_e32 v31, 1.0, v31
	v_rcp_f32_e32 v24, v24
	v_rcp_f32_e32 v25, v25
	v_rcp_f32_e32 v26, v26
	v_rcp_f32_e32 v27, v27
	v_rcp_f32_e32 v28, v28
	v_rcp_f32_e32 v29, v29
	v_rcp_f32_e32 v30, v30
	v_rcp_f32_e32 v31, v31
	s_waitcnt lgkmcnt(4)
	v_pk_mul_f32 v[0:1], v[0:1], v[14:15] op_sel_hi:[1,0]
	v_pk_mul_f32 v[2:3], v[2:3], v[14:15] op_sel_hi:[1,0]
	v_pk_mul_f32 v[4:5], v[4:5], v[14:15] op_sel_hi:[1,0]
	v_pk_mul_f32 v[6:7], v[6:7], v[14:15] op_sel_hi:[1,0]
	v_pk_mul_f32 v[0:1], v[16:17], v[0:1]
	v_pk_mul_f32 v[2:3], v[18:19], v[2:3]
	v_pk_mul_f32 v[4:5], v[20:21], v[4:5]
	v_pk_mul_f32 v[6:7], v[22:23], v[6:7]
	v_pk_mul_f32 v[0:1], v[24:25], v[0:1]
	v_pk_mul_f32 v[2:3], v[26:27], v[2:3]
	v_pk_mul_f32 v[4:5], v[28:29], v[4:5]
	v_pk_mul_f32 v[6:7], v[30:31], v[6:7]
	v_cvt_pk_bf16_f32 v8, v0, v1
	v_cvt_pk_bf16_f32 v9, v2, v3
	v_cvt_pk_bf16_f32 v10, v4, v5
	v_cvt_pk_bf16_f32 v11, v6, v7
	global_store_dwordx4 v[200:201], v[8:11], off offset:32
	ds_read_b128 v[0:3], v167 offset:128
	ds_read_b128 v[4:7], v167 offset:144
	ds_read_b128 v[16:19], v138 offset:62592
	ds_read_b128 v[20:23], v138 offset:62608
	s_waitcnt vmcnt(5)
	v_lshlrev_b32_e32 v24, 16, v218
	v_and_b32_e32 v25, 0xffff0000, v218
	v_lshlrev_b32_e32 v26, 16, v219
	v_and_b32_e32 v27, 0xffff0000, v219
	v_lshlrev_b32_e32 v28, 16, v220
	v_and_b32_e32 v29, 0xffff0000, v220
	v_lshlrev_b32_e32 v30, 16, v221
	v_and_b32_e32 v31, 0xffff0000, v221
	v_mul_f32_e32 v24, 0xbfb8aa3b, v24
	v_mul_f32_e32 v25, 0xbfb8aa3b, v25
	v_mul_f32_e32 v26, 0xbfb8aa3b, v26
	v_mul_f32_e32 v27, 0xbfb8aa3b, v27
	v_mul_f32_e32 v28, 0xbfb8aa3b, v28
	v_mul_f32_e32 v29, 0xbfb8aa3b, v29
	v_mul_f32_e32 v30, 0xbfb8aa3b, v30
	v_mul_f32_e32 v31, 0xbfb8aa3b, v31
	v_exp_f32_e32 v24, v24
	v_exp_f32_e32 v25, v25
	v_exp_f32_e32 v26, v26
	v_exp_f32_e32 v27, v27
	v_exp_f32_e32 v28, v28
	v_exp_f32_e32 v29, v29
	v_exp_f32_e32 v30, v30
	v_exp_f32_e32 v31, v31
	v_add_f32_e32 v24, 1.0, v24
	v_add_f32_e32 v25, 1.0, v25
	v_add_f32_e32 v26, 1.0, v26
	v_add_f32_e32 v27, 1.0, v27
	v_add_f32_e32 v28, 1.0, v28
	v_add_f32_e32 v29, 1.0, v29
	v_add_f32_e32 v30, 1.0, v30
	v_add_f32_e32 v31, 1.0, v31
	v_rcp_f32_e32 v24, v24
	v_rcp_f32_e32 v25, v25
	v_rcp_f32_e32 v26, v26
	v_rcp_f32_e32 v27, v27
	v_rcp_f32_e32 v28, v28
	v_rcp_f32_e32 v29, v29
	v_rcp_f32_e32 v30, v30
	v_rcp_f32_e32 v31, v31
	s_waitcnt lgkmcnt(4)
	v_pk_mul_f32 v[32:33], v[32:33], v[14:15] op_sel_hi:[1,0]
	v_pk_mul_f32 v[34:35], v[34:35], v[14:15] op_sel_hi:[1,0]
	v_pk_mul_f32 v[36:37], v[36:37], v[14:15] op_sel_hi:[1,0]
	v_pk_mul_f32 v[38:39], v[38:39], v[14:15] op_sel_hi:[1,0]
	v_pk_mul_f32 v[32:33], v[40:41], v[32:33]
	v_pk_mul_f32 v[34:35], v[42:43], v[34:35]
	v_pk_mul_f32 v[36:37], v[44:45], v[36:37]
	v_pk_mul_f32 v[38:39], v[46:47], v[38:39]
	v_pk_mul_f32 v[32:33], v[24:25], v[32:33]
	v_pk_mul_f32 v[34:35], v[26:27], v[34:35]
	v_pk_mul_f32 v[36:37], v[28:29], v[36:37]
	v_pk_mul_f32 v[38:39], v[30:31], v[38:39]
	v_cvt_pk_bf16_f32 v8, v32, v33
	v_cvt_pk_bf16_f32 v9, v34, v35
	v_cvt_pk_bf16_f32 v10, v36, v37
	v_cvt_pk_bf16_f32 v11, v38, v39
	global_store_dwordx4 v[200:201], v[8:11], off offset:48
	ds_read_b128 v[32:35], v167 offset:160
	ds_read_b128 v[36:39], v167 offset:176
	ds_read_b128 v[40:43], v138 offset:62624
	ds_read_b128 v[44:47], v138 offset:62640
	s_waitcnt vmcnt(5)
	v_lshlrev_b32_e32 v24, 16, v222
	v_and_b32_e32 v25, 0xffff0000, v222
	v_lshlrev_b32_e32 v26, 16, v223
	v_and_b32_e32 v27, 0xffff0000, v223
	v_lshlrev_b32_e32 v28, 16, v224
	v_and_b32_e32 v29, 0xffff0000, v224
	v_lshlrev_b32_e32 v30, 16, v225
	v_and_b32_e32 v31, 0xffff0000, v225
	v_mul_f32_e32 v24, 0xbfb8aa3b, v24
	v_mul_f32_e32 v25, 0xbfb8aa3b, v25
	v_mul_f32_e32 v26, 0xbfb8aa3b, v26
	v_mul_f32_e32 v27, 0xbfb8aa3b, v27
	v_mul_f32_e32 v28, 0xbfb8aa3b, v28
	v_mul_f32_e32 v29, 0xbfb8aa3b, v29
	v_mul_f32_e32 v30, 0xbfb8aa3b, v30
	v_mul_f32_e32 v31, 0xbfb8aa3b, v31
	v_exp_f32_e32 v24, v24
	v_exp_f32_e32 v25, v25
	v_exp_f32_e32 v26, v26
	v_exp_f32_e32 v27, v27
	v_exp_f32_e32 v28, v28
	v_exp_f32_e32 v29, v29
	v_exp_f32_e32 v30, v30
	v_exp_f32_e32 v31, v31
	v_add_f32_e32 v24, 1.0, v24
	v_add_f32_e32 v25, 1.0, v25
	v_add_f32_e32 v26, 1.0, v26
	v_add_f32_e32 v27, 1.0, v27
	v_add_f32_e32 v28, 1.0, v28
	v_add_f32_e32 v29, 1.0, v29
	v_add_f32_e32 v30, 1.0, v30
	v_add_f32_e32 v31, 1.0, v31
	v_rcp_f32_e32 v24, v24
	v_rcp_f32_e32 v25, v25
	v_rcp_f32_e32 v26, v26
	v_rcp_f32_e32 v27, v27
	v_rcp_f32_e32 v28, v28
	v_rcp_f32_e32 v29, v29
	v_rcp_f32_e32 v30, v30
	v_rcp_f32_e32 v31, v31
	s_waitcnt lgkmcnt(4)
	v_pk_mul_f32 v[0:1], v[0:1], v[14:15] op_sel_hi:[1,0]
	v_pk_mul_f32 v[2:3], v[2:3], v[14:15] op_sel_hi:[1,0]
	v_pk_mul_f32 v[4:5], v[4:5], v[14:15] op_sel_hi:[1,0]
	v_pk_mul_f32 v[6:7], v[6:7], v[14:15] op_sel_hi:[1,0]
	v_pk_mul_f32 v[0:1], v[16:17], v[0:1]
	v_pk_mul_f32 v[2:3], v[18:19], v[2:3]
	v_pk_mul_f32 v[4:5], v[20:21], v[4:5]
	v_pk_mul_f32 v[6:7], v[22:23], v[6:7]
	v_pk_mul_f32 v[0:1], v[24:25], v[0:1]
	v_pk_mul_f32 v[2:3], v[26:27], v[2:3]
	v_pk_mul_f32 v[4:5], v[28:29], v[4:5]
	v_pk_mul_f32 v[6:7], v[30:31], v[6:7]
	v_cvt_pk_bf16_f32 v8, v0, v1
	v_cvt_pk_bf16_f32 v9, v2, v3
	v_cvt_pk_bf16_f32 v10, v4, v5
	v_cvt_pk_bf16_f32 v11, v6, v7
	global_store_dwordx4 v[200:201], v[8:11], off offset:64
	s_waitcnt vmcnt(5)
	v_lshlrev_b32_e32 v24, 16, v226
	v_and_b32_e32 v25, 0xffff0000, v226
	v_lshlrev_b32_e32 v26, 16, v227
	v_and_b32_e32 v27, 0xffff0000, v227
	v_lshlrev_b32_e32 v28, 16, v228
	v_and_b32_e32 v29, 0xffff0000, v228
	v_lshlrev_b32_e32 v30, 16, v229
	v_and_b32_e32 v31, 0xffff0000, v229
	v_mul_f32_e32 v24, 0xbfb8aa3b, v24
	v_mul_f32_e32 v25, 0xbfb8aa3b, v25
	v_mul_f32_e32 v26, 0xbfb8aa3b, v26
	v_mul_f32_e32 v27, 0xbfb8aa3b, v27
	v_mul_f32_e32 v28, 0xbfb8aa3b, v28
	v_mul_f32_e32 v29, 0xbfb8aa3b, v29
	v_mul_f32_e32 v30, 0xbfb8aa3b, v30
	v_mul_f32_e32 v31, 0xbfb8aa3b, v31
	v_exp_f32_e32 v24, v24
	v_exp_f32_e32 v25, v25
	v_exp_f32_e32 v26, v26
	v_exp_f32_e32 v27, v27
	v_exp_f32_e32 v28, v28
	v_exp_f32_e32 v29, v29
	v_exp_f32_e32 v30, v30
	v_exp_f32_e32 v31, v31
	v_add_f32_e32 v24, 1.0, v24
	v_add_f32_e32 v25, 1.0, v25
	v_add_f32_e32 v26, 1.0, v26
	v_add_f32_e32 v27, 1.0, v27
	v_add_f32_e32 v28, 1.0, v28
	v_add_f32_e32 v29, 1.0, v29
	v_add_f32_e32 v30, 1.0, v30
	v_add_f32_e32 v31, 1.0, v31
	v_rcp_f32_e32 v24, v24
	v_rcp_f32_e32 v25, v25
	v_rcp_f32_e32 v26, v26
	v_rcp_f32_e32 v27, v27
	v_rcp_f32_e32 v28, v28
	v_rcp_f32_e32 v29, v29
	v_rcp_f32_e32 v30, v30
	v_rcp_f32_e32 v31, v31
	s_waitcnt lgkmcnt(0)
	v_pk_mul_f32 v[32:33], v[32:33], v[14:15] op_sel_hi:[1,0]
	v_pk_mul_f32 v[34:35], v[34:35], v[14:15] op_sel_hi:[1,0]
	v_pk_mul_f32 v[36:37], v[36:37], v[14:15] op_sel_hi:[1,0]
	v_pk_mul_f32 v[38:39], v[38:39], v[14:15] op_sel_hi:[1,0]
	v_pk_mul_f32 v[32:33], v[40:41], v[32:33]
	v_pk_mul_f32 v[34:35], v[42:43], v[34:35]
	v_pk_mul_f32 v[36:37], v[44:45], v[36:37]
	v_pk_mul_f32 v[38:39], v[46:47], v[38:39]
	v_pk_mul_f32 v[32:33], v[24:25], v[32:33]
	v_pk_mul_f32 v[34:35], v[26:27], v[34:35]
	v_pk_mul_f32 v[36:37], v[28:29], v[36:37]
	v_pk_mul_f32 v[38:39], v[30:31], v[38:39]
	v_cvt_pk_bf16_f32 v8, v32, v33
	v_cvt_pk_bf16_f32 v9, v34, v35
	v_cvt_pk_bf16_f32 v10, v36, v37
	v_cvt_pk_bf16_f32 v11, v38, v39
	global_store_dwordx4 v[200:201], v[8:11], off offset:80
	s_cbranch_scc0 .LBB0_561

.LBB0_511:
	s_or_b64 exec, exec, s[36:37]
	v_mul_u32_u24_e32 v175, 0xc0, v0
	v_readlane_b32 s100, v250, 13
	v_readlane_b32 s101, v250, 14
	v_min_u32_e32 v246, 0xbf, v88
	v_add_lshl_u32 v246, v175, v246, 2
	s_nop 2
	global_load_dword v246, v246, s[100:101]
	s_mov_b32 s64, 0
	v_mov_b32_e32 v69, v88
	s_branch .LBB0_513
